# per-XCD work queues in phase 2 (each XCD owns one batch: 16 scans + 256 attention items ordered in waves of 4 heads x 8 q-blocks)
# baseline (speedup 1.0000x reference)
; #define LAUNDER_TID(t) int t = (g_wave << 6) | (int)__builtin_amdgcn_mbcnt_hi(~0u, __builtin_amdgcn_mbcnt_lo(~0u, 0u)); asm volatile("" : "+v"(t))
; DI void phase0(const Params& p, char* smem, const int g_wave) {
;   LAUNDER_TID(tid);
;   const int lane = tid & 63, wid = tid >> 6;
;   const int gw = blockIdx.x * 8 + wid, nw = gridDim.x * 8;
;   const long gt = (long)blockIdx.x * 512 + tid, nt = (long)gridDim.x * 512;
;   if (blockIdx.x == 0 && tid == 0) { ((int*)(p.ws + WS_CTR))[0] = 0; }
; __global__ void __launch_bounds__(512) mega(Params p) {
;   extern __shared__ __attribute__((aligned(16))) char smem[];
;   cg::grid_group grid = cg::this_grid();
;   const int lo = (int)p.ph_lo, hi = (int)p.ph_hi;
;   const int g_wave = __builtin_amdgcn_readfirstlane(threadIdx.x >> 6);
;   if (lo <= 0 && hi > 0) { phase0(p, smem, g_wave); if (hi > 1) grid.sync(); }
_Z4mega6Params:
	s_load_dwordx16 s[12:27], s[0:1], 0x0
	s_load_dwordx16 s[36:51], s[0:1], 0x40
	s_load_dwordx16 s[52:67], s[0:1], 0x80
	s_load_dwordx8 s[68:75], s[0:1], 0xc0
	v_writelane_b32 v255, s2, 0
	v_and_b32_e32 v218, 0x3ff, v0
	v_mbcnt_lo_u32_b32 v1, -1, 0
	v_writelane_b32 v255, s3, 1
	s_add_u32 s2, s0, 0xe8
	s_load_dwordx2 s[84:85], s[0:1], 0xe0
	s_nop 0
	s_load_dword s0, s[0:1], 0xe8
	s_addc_u32 s3, s1, 0
	v_writelane_b32 v255, s2, 2
	s_waitcnt lgkmcnt(0)
	s_cmp_lt_i32 s74, 1
	v_readfirstlane_b32 s75, v218
	v_writelane_b32 v255, s3, 3
	v_writelane_b32 v255, s0, 4
	s_nop 1
	v_writelane_b32 v255, s1, 5
	s_cselect_b64 s[0:1], -1, 0
	s_cmp_gt_i32 s84, 0
	s_cselect_b64 s[2:3], -1, 0
	s_and_b64 s[0:1], s[0:1], s[2:3]
	s_andn2_b64 vcc, exec, s[0:1]
	s_mov_b32 s0, s84
	v_writelane_b32 v255, s0, 6
	s_nop 1
	v_writelane_b32 v255, s1, 7
	s_cbranch_vccnz .LBB0_69
	s_and_b32 s0, s75, 0xffffffc0
	v_mbcnt_hi_u32_b32 v33, -1, v1
	v_or_b32_e32 v32, s0, v33
	v_mov_b32_e32 v4, v32
	v_readlane_b32 s0, v255, 0
	v_readlane_b32 s1, v255, 1
	s_nop 0
	v_or_b32_e32 v2, s0, v4
	v_cmp_eq_u32_e32 vcc, 0, v2
	s_and_saveexec_b64 s[0:1], vcc
	s_cbranch_execz .LBB0_3
	v_mov_b32_e32 v2, 0
	global_store_dword v2, v2, s[72:73]
	global_store_dword v2, v2, s[72:73] offset:128
	global_store_dword v2, v2, s[72:73] offset:256
	global_store_dword v2, v2, s[72:73] offset:384
	global_store_dword v2, v2, s[72:73] offset:512
	global_store_dword v2, v2, s[72:73] offset:640
	global_store_dword v2, v2, s[72:73] offset:768
	global_store_dword v2, v2, s[72:73] offset:896

; #define LAUNDER_TID(t) int t = (g_wave << 6) | (int)__builtin_amdgcn_mbcnt_hi(~0u, __builtin_amdgcn_mbcnt_lo(~0u, 0u)); asm volatile("" : "+v"(t))
; DI void phase2(const Params& p, char* smem, const int g_wave) {
;     ...
;     { LAUNDER_TID(tq); if (tq == 0) s_item = atomicAdd(ctr, 1); }
;     __syncthreads();
.LBB0_683:
	v_mov_b32_e32 v2, v196
	s_nop 0
	v_cmp_eq_u32_e32 vcc, 0, v2
	s_and_saveexec_b64 s[0:1], vcc
	s_cbranch_execz .LBB0_687
	s_mov_b64 s[34:35], exec
	v_mbcnt_lo_u32_b32 v2, s34, 0
	v_mbcnt_hi_u32_b32 v2, s35, v2
	v_cmp_eq_u32_e32 vcc, 0, v2
	s_and_saveexec_b64 s[4:5], vcc
	s_cbranch_execz .LBB0_686
	s_bcnt1_i32_b64 s6, s[34:35]
	v_mov_b32_e32 v4, s6
	v_readlane_b32 s34, v255, 0
	s_nop 3
	s_and_b32 s34, s34, 7
	s_lshl_b32 s34, s34, 7
	v_mov_b32_e32 v6, s34
	s_nop 0
	global_atomic_add v4, v6, v4, s[72:73] sc0

; DI void phase2(const Params& p, char* smem, const int g_wave) {
;     ...
;   constexpr int N0 = 128, N1 = N0 + 2048, N2 = N1 + 128, N3 = N2 + 64;
;     ...
;     const int it = __builtin_amdgcn_readfirstlane(s_item);
;     __syncthreads();
;     if (it >= N3) break;
;     const bool is_scan = it < N0 || (it >= N1 && it < N2);
;     if (is_scan) {
.LBB0_687:
	s_or_b64 exec, exec, s[0:1]
	s_waitcnt lgkmcnt(0)
	s_barrier
	ds_read_b32 v2, v3 offset:4
	s_mov_b64 s[0:1], -1
	s_waitcnt lgkmcnt(0)
	s_barrier
	v_readfirstlane_b32 s6, v2
	v_readlane_b32 s4, v255, 0
	s_nop 3
	s_and_b32 s4, s4, 7
	s_lshl_b32 s5, s4, 4
	s_movk_i32 s78, 0x940
	s_lshl_b32 s50, s4, 3
	s_add_i32 s50, s50, s6
	s_addk_i32 s50, 0x7e0
	s_cmp_lt_u32 s6, 0x128
	s_cselect_b32 s78, s50, s78
	s_add_i32 s50, s5, s6
	s_addk_i32 s50, 0x770
	s_cmp_lt_u32 s6, 0x120
	s_cselect_b32 s78, s50, s78
	s_lshl_b32 s50, s4, 8
	s_add_i32 s50, s50, s6
	s_addk_i32 s50, 0x70
	s_cmp_lt_u32 s6, 0x110
	s_cselect_b32 s78, s50, s78
	s_add_i32 s50, s5, s6
	s_cmp_lt_u32 s6, 16
	s_cselect_b32 s78, s50, s78
	s_mov_b32 s6, s78
	s_cmpk_gt_i32 s6, 0x93f
	s_cbranch_scc1 .LBB0_682
	s_cmpk_lt_i32 s6, 0x80
	s_cselect_b64 s[38:39], -1, 0
	s_cmpk_gt_i32 s6, 0x7f
	s_cselect_b64 s[40:41], -1, 0
	s_and_b32 s0, s6, 0x7fffff80
	s_cmpk_lg_i32 s0, 0x880
	s_cselect_b64 s[0:1], -1, 0
	s_and_b64 s[4:5], s[40:41], s[0:1]
	s_mov_b64 s[0:1], -1
	s_and_b64 vcc, exec, s[4:5]
	s_cbranch_vccz .LBB0_721
	s_cmpk_lt_u32 s6, 0x880
	s_cselect_b64 s[54:55], -1, 0
	s_cmpk_gt_u32 s6, 0x87f
	s_cselect_b64 s[0:1], -1, 0
	s_mov_b64 s[4:5], -1
	s_and_b64 vcc, exec, s[0:1]
	s_cbranch_vccz .LBB0_691
	s_add_i32 s50, s6, 0xfffff700
	s_mov_b32 s78, 0
	s_cbranch_execnz .LBB0_693
	s_branch .LBB0_692

; DI void phase2(const Params& p, char* smem, const int g_wave) {
;     ...
;       const bool prm = it < N1;
;       int qb, bh;
;       if (prm) { int a = it - N0; qb = 31 - (a >> 6); bh = a & 63; } else { qb = 0; bh = it - N2; }
;       const int b = bh >> 3, h = bh & 7;
.LBB0_692:
	s_add_i32 s4, s6, 0xffffff80
	s_and_b32 s5, s4, 7
	s_bfe_u32 s50, s4, 0x20006
	s_lshl_b32 s50, s50, 3
	s_add_i32 s5, s5, s50
	s_sub_i32 s78, 31, s5
	s_bfe_u32 s50, s4, 0x20003
	s_bfe_u32 s5, s4, 0x10005
	s_lshl_b32 s5, s5, 2
	s_add_i32 s50, s50, s5
	s_lshr_b32 s5, s4, 8
	s_lshl_b32 s5, s5, 3
	s_add_i32 s50, s50, s5
